# rwb n-tile loop hand-written and software-pipelined: next step's MFMAs and the LDS reads of the step after run under the current step's VALU epilogue (same operations, bit-identical)
# baseline (speedup 1.0000x reference)
; #define LAS __attribute__((address_space(3)))
; __device__ __forceinline__ f32x4 mfma16(h8 a, h8 b, f32x4 c) { return __builtin_amdgcn_mfma_f32_16x16x32_f16(a, b, c, 0, 0, 0); }
; __device__ __forceinline__ void phase_rwb(const int wvs, const Params& p, LAS unsigned char* lds, int layer) {
;     ...
;     for (int nt = 0; nt < 24; ++nt) { f32x4 aw = {0.f, 0.f, 0.f, 0.f}, aa = {0.f, 0.f, 0.f, 0.f};
;       const int n4 = nt * 16 + fq * 4; const f32x4 w04 = *(const f32x4*)(w0 + n4), a04 = *(const f32x4*)(a0 + n4);
; #pragma unroll
;       for (int ks = 0; ks < 2; ++ks) { aw = mfma16(*(const LAS h8*)(lds + (nt * 16 + fr) * 144 + ks * 64 + fq * 16), bw[ks], aw); aa = mfma16(*(const LAS h8*)(lds + 55296 + (nt * 16 + fr) * 144 + ks * 64 + fq * 16), ba[ks], aa); }
.Lrwb_go:
	ds_read_b128 v[112:115], v32 offset:0
	ds_read_b128 v[120:123], v32 offset:55296
	ds_read_b128 v[116:119], v32 offset:64
	ds_read_b128 v[124:127], v32 offset:55360
	ds_read_b128 v[128:131], v106 offset:0
	ds_read_b128 v[132:135], v106 offset:1536
	ds_read_b128 v[136:139], v32 offset:2304
	ds_read_b128 v[144:147], v32 offset:57600
	ds_read_b128 v[140:143], v32 offset:2368
	ds_read_b128 v[148:151], v32 offset:57664
	ds_read_b128 v[152:155], v106 offset:64
	ds_read_b128 v[156:159], v106 offset:1600
	s_waitcnt lgkmcnt(6)
	v_mfma_f32_16x16x32_f16 v[34:37], v[112:115], v[2:5], 0
	v_mfma_f32_16x16x32_f16 v[38:41], v[120:123], v[6:9], 0
	v_mfma_f32_16x16x32_f16 v[34:37], v[116:119], v[10:13], v[34:37]
	v_mfma_f32_16x16x32_f16 v[38:41], v[124:127], v[14:17], v[38:41]
	s_nop 7
	s_nop 7
; #define LAS __attribute__((address_space(3)))
; __device__ __forceinline__ float sigmoidf_(float x) { return __builtin_amdgcn_rcpf(1.0f + __expf(-x)); }
; __device__ __forceinline__ float softplusf_(float x) { return x > 20.f ? x : __logf(1.0f + __expf(x)); }
; __device__ __forceinline__ f32x4 mfma16(h8 a, h8 b, f32x4 c) { return __builtin_amdgcn_mfma_f32_16x16x32_f16(a, b, c, 0, 0, 0); }
; __device__ __forceinline__ void phase_rwb(const int wvs, const Params& p, LAS unsigned char* lds, int layer) {
;     ...
;     for (int nt = 0; nt < 24; ++nt) { f32x4 aw = {0.f, 0.f, 0.f, 0.f}, aa = {0.f, 0.f, 0.f, 0.f};
;       const int n4 = nt * 16 + fq * 4; const f32x4 w04 = *(const f32x4*)(w0 + n4), a04 = *(const f32x4*)(a0 + n4);
; #pragma unroll
;       for (int ks = 0; ks < 2; ++ks) { aw = mfma16(*(const LAS h8*)(lds + (nt * 16 + fr) * 144 + ks * 64 + fq * 16), bw[ks], aw); aa = mfma16(*(const LAS h8*)(lds + 55296 + (nt * 16 + fr) * 144 + ks * 64 + fq * 16), ba[ks], aa); }
;       h4 oe, oa;
; #pragma unroll
;       for (int r = 0; r < 4; ++r) { const float wl = -softplusf_(-(w04[r] + aw[r])) - 0.5f; oe[r] = (hf)__expf(wl); oa[r] = (hf)sigmoidf_(a04[r] + aa[r]); }
;       *(h4*)(P + tok * PP + PC_EF + d * 384 + n4) = oe; *(h4*)(P + tok * PP + PC_AF + d * 384 + n4) = oa; }
.LBB0_1146:
	v_add_f32_e32 v22, v132, v38
	v_add_f32_e32 v23, v133, v39
	v_add_f32_e32 v24, v134, v40
	v_add_f32_e32 v25, v135, v41
	v_add_f32_e32 v18, v128, v34
	v_add_f32_e32 v19, v129, v35
	v_add_f32_e32 v20, v130, v36
	v_add_f32_e32 v21, v131, v37
	s_waitcnt lgkmcnt(0)
	v_mfma_f32_16x16x32_f16 v[34:37], v[136:139], v[2:5], 0
	v_mfma_f32_16x16x32_f16 v[38:41], v[144:147], v[6:9], 0
	v_mfma_f32_16x16x32_f16 v[34:37], v[140:143], v[10:13], v[34:37]
	v_mfma_f32_16x16x32_f16 v[38:41], v[148:151], v[14:17], v[38:41]
	ds_read_b128 v[112:115], v32 offset:4608
	ds_read_b128 v[120:123], v32 offset:59904
	ds_read_b128 v[116:119], v32 offset:4672
	ds_read_b128 v[124:127], v32 offset:59968
	ds_read_b128 v[128:131], v106 offset:128
	ds_read_b128 v[132:135], v106 offset:1664
	v_mul_f32_e32 v42, 0xbfb8aa3b, v18
	v_mul_f32_e32 v43, 0xbfb8aa3b, v19
	v_mul_f32_e32 v44, 0xbfb8aa3b, v20
	v_mul_f32_e32 v45, 0xbfb8aa3b, v21
	v_exp_f32_e32 v42, v42
	v_exp_f32_e32 v43, v43
	v_exp_f32_e32 v44, v44
	v_exp_f32_e32 v45, v45
	v_add_f32_e32 v42, 1.0, v42
	v_add_f32_e32 v43, 1.0, v43
	v_add_f32_e32 v44, 1.0, v44
	v_add_f32_e32 v45, 1.0, v45
	v_log_f32_e32 v42, v42
	v_log_f32_e32 v43, v43
	v_log_f32_e32 v44, v44
	v_log_f32_e32 v45, v45
	v_mul_f32_e32 v22, 0xbfb8aa3b, v22
	v_mul_f32_e32 v23, 0xbfb8aa3b, v23
	v_mul_f32_e32 v24, 0xbfb8aa3b, v24
	v_mul_f32_e32 v25, 0xbfb8aa3b, v25
	v_mul_f32_e32 v46, 0x3f317217, v42
	v_mul_f32_e32 v47, 0x3f317217, v43
	v_mul_f32_e32 v48, 0x3f317217, v44
	v_mul_f32_e32 v49, 0x3f317217, v45
	v_fma_f32 v46, v42, s66, -v46
	v_fma_f32 v47, v43, s66, -v47
	v_fma_f32 v48, v44, s66, -v48
	v_fma_f32 v49, v45, s66, -v49
	v_fmac_f32_e32 v46, 0x3377d1cf, v42
	v_fmac_f32_e32 v47, 0x3377d1cf, v43
	v_fmac_f32_e32 v48, 0x3377d1cf, v44
	v_fmac_f32_e32 v49, 0x3377d1cf, v45
	v_fmac_f32_e32 v46, 0x3f317217, v42
	v_fmac_f32_e32 v47, 0x3f317217, v43
	v_fmac_f32_e32 v48, 0x3f317217, v44
	v_fmac_f32_e32 v49, 0x3f317217, v45
	v_cmp_gt_f32_e32 vcc, s71, v18
	v_cmp_gt_f32_e64 s[4:5], s71, v19
	v_cmp_gt_f32_e64 s[6:7], s71, v20
	v_exp_f32_e32 v22, v22
	v_cndmask_b32_e64 v18, v46, -v18, vcc
	v_cmp_gt_f32_e32 vcc, s71, v21
	v_cndmask_b32_e64 v19, v47, -v19, s[4:5]
	v_cndmask_b32_e64 v20, v48, -v20, s[6:7]
	v_exp_f32_e32 v23, v23
	v_cndmask_b32_e64 v21, v49, -v21, vcc
	v_exp_f32_e32 v24, v24
	v_exp_f32_e32 v25, v25
	v_sub_f32_e32 v18, -0.5, v18
	v_sub_f32_e32 v19, -0.5, v19
	v_sub_f32_e32 v20, -0.5, v20
	v_sub_f32_e32 v21, -0.5, v21
	v_mul_f32_e32 v18, 0x3fb8aa3b, v18
	v_mul_f32_e32 v19, 0x3fb8aa3b, v19
	v_mul_f32_e32 v20, 0x3fb8aa3b, v20
	v_mul_f32_e32 v21, 0x3fb8aa3b, v21
	v_exp_f32_e32 v18, v18
	v_exp_f32_e32 v19, v19
	v_exp_f32_e32 v20, v20
	v_exp_f32_e32 v21, v21
	v_add_f32_e32 v22, 1.0, v22
	v_add_f32_e32 v23, 1.0, v23
	v_add_f32_e32 v24, 1.0, v24
	v_add_f32_e32 v25, 1.0, v25
	v_rcp_f32_e32 v22, v22
	v_rcp_f32_e32 v23, v23
	v_rcp_f32_e32 v24, v24
	v_rcp_f32_e32 v25, v25
	s_nop 0
	v_cvt_pk_f16_f32 v18, v18, v19
	v_cvt_pk_f16_f32 v19, v20, v21
	v_cvt_pk_f16_f32 v20, v22, v23
	v_cvt_pk_f16_f32 v21, v24, v25
	global_store_dwordx2 v[26:27], v[18:19], off offset:-1536
	global_store_dwordx2 v[26:27], v[20:21], off
	v_add_f32_e32 v22, v156, v38
	v_add_f32_e32 v23, v157, v39
	v_add_f32_e32 v24, v158, v40
	v_add_f32_e32 v25, v159, v41
	v_add_f32_e32 v18, v152, v34
	v_add_f32_e32 v19, v153, v35
	v_add_f32_e32 v20, v154, v36
	v_add_f32_e32 v21, v155, v37
	s_waitcnt lgkmcnt(0)
	v_mfma_f32_16x16x32_f16 v[34:37], v[112:115], v[2:5], 0
	v_mfma_f32_16x16x32_f16 v[38:41], v[120:123], v[6:9], 0
	v_mfma_f32_16x16x32_f16 v[34:37], v[116:119], v[10:13], v[34:37]
	v_mfma_f32_16x16x32_f16 v[38:41], v[124:127], v[14:17], v[38:41]
	ds_read_b128 v[136:139], v32 offset:6912
	ds_read_b128 v[144:147], v32 offset:62208
	ds_read_b128 v[140:143], v32 offset:6976
	ds_read_b128 v[148:151], v32 offset:62272
	ds_read_b128 v[152:155], v106 offset:192
	ds_read_b128 v[156:159], v106 offset:1728
	v_mul_f32_e32 v42, 0xbfb8aa3b, v18
	v_mul_f32_e32 v43, 0xbfb8aa3b, v19
	v_mul_f32_e32 v44, 0xbfb8aa3b, v20
	v_mul_f32_e32 v45, 0xbfb8aa3b, v21
	v_exp_f32_e32 v42, v42
	v_exp_f32_e32 v43, v43
	v_exp_f32_e32 v44, v44
	v_exp_f32_e32 v45, v45
	v_add_f32_e32 v42, 1.0, v42
	v_add_f32_e32 v43, 1.0, v43
	v_add_f32_e32 v44, 1.0, v44
	v_add_f32_e32 v45, 1.0, v45
	v_log_f32_e32 v42, v42
	v_log_f32_e32 v43, v43
	v_log_f32_e32 v44, v44
	v_log_f32_e32 v45, v45
	v_mul_f32_e32 v22, 0xbfb8aa3b, v22
	v_mul_f32_e32 v23, 0xbfb8aa3b, v23
	v_mul_f32_e32 v24, 0xbfb8aa3b, v24
	v_mul_f32_e32 v25, 0xbfb8aa3b, v25
	v_mul_f32_e32 v46, 0x3f317217, v42
	v_mul_f32_e32 v47, 0x3f317217, v43
	v_mul_f32_e32 v48, 0x3f317217, v44
	v_mul_f32_e32 v49, 0x3f317217, v45
	v_fma_f32 v46, v42, s66, -v46
	v_fma_f32 v47, v43, s66, -v47
	v_fma_f32 v48, v44, s66, -v48
	v_fma_f32 v49, v45, s66, -v49
	v_fmac_f32_e32 v46, 0x3377d1cf, v42
	v_fmac_f32_e32 v47, 0x3377d1cf, v43
	v_fmac_f32_e32 v48, 0x3377d1cf, v44
	v_fmac_f32_e32 v49, 0x3377d1cf, v45
	v_fmac_f32_e32 v46, 0x3f317217, v42
	v_fmac_f32_e32 v47, 0x3f317217, v43
	v_fmac_f32_e32 v48, 0x3f317217, v44
	v_fmac_f32_e32 v49, 0x3f317217, v45
	v_cmp_gt_f32_e32 vcc, s71, v18
	v_cmp_gt_f32_e64 s[4:5], s71, v19
	v_cmp_gt_f32_e64 s[6:7], s71, v20
	v_exp_f32_e32 v22, v22
	v_cndmask_b32_e64 v18, v46, -v18, vcc
	v_cmp_gt_f32_e32 vcc, s71, v21
	v_cndmask_b32_e64 v19, v47, -v19, s[4:5]
	v_cndmask_b32_e64 v20, v48, -v20, s[6:7]
	v_exp_f32_e32 v23, v23
	v_cndmask_b32_e64 v21, v49, -v21, vcc
	v_exp_f32_e32 v24, v24
	v_exp_f32_e32 v25, v25
	v_sub_f32_e32 v18, -0.5, v18
	v_sub_f32_e32 v19, -0.5, v19
	v_sub_f32_e32 v20, -0.5, v20
	v_sub_f32_e32 v21, -0.5, v21
	v_mul_f32_e32 v18, 0x3fb8aa3b, v18
	v_mul_f32_e32 v19, 0x3fb8aa3b, v19
	v_mul_f32_e32 v20, 0x3fb8aa3b, v20
	v_mul_f32_e32 v21, 0x3fb8aa3b, v21
	v_exp_f32_e32 v18, v18
	v_exp_f32_e32 v19, v19
	v_exp_f32_e32 v20, v20
	v_exp_f32_e32 v21, v21
	v_add_f32_e32 v22, 1.0, v22
	v_add_f32_e32 v23, 1.0, v23
	v_add_f32_e32 v24, 1.0, v24
	v_add_f32_e32 v25, 1.0, v25
	v_rcp_f32_e32 v22, v22
	v_rcp_f32_e32 v23, v23
	v_rcp_f32_e32 v24, v24
	v_rcp_f32_e32 v25, v25
	s_nop 0
	v_cvt_pk_f16_f32 v18, v18, v19
	v_cvt_pk_f16_f32 v19, v20, v21
	v_cvt_pk_f16_f32 v20, v22, v23
	v_cvt_pk_f16_f32 v21, v24, v25
	global_store_dwordx2 v[26:27], v[18:19], off offset:-1504
	global_store_dwordx2 v[26:27], v[20:21], off offset:32
	v_lshl_add_u64 v[26:27], v[26:27], 0, 64
	v_add_u32_e32 v32, 0x1200, v32
	v_add_u32_e32 v106, 0x80, v106
	s_add_u32 s14, s14, 0x80
	s_addc_u32 s15, s15, 0
	s_cmpk_eq_i32 s14, 0x600
	s_cbranch_scc0 .LBB0_1146
	s_waitcnt lgkmcnt(0)
	s_mov_b32 s6, 1
	s_mov_b64 s[4:5], 0
	s_and_b64 vcc, exec, s[12:13]
	s_cbranch_vccz .LBB0_1145
